# scan loop: wave-uniform branch test shortened (7.12): branch on SCC directly instead of cselect/and/vccnz
# baseline (speedup 1.0000x reference)
; __device__ __forceinline__ void rwkv_unit(LAS unsigned char* lds, const LAS Params* PL, int b, int h, const int tid) {
;     ...
; #pragma unroll 2
;             for (int tl = 0; tl < TC; tl += 2) {
;                 RW_LV(Q, tl + 1);
;                 RW_ROW2(P, tl * 64);
;                 if (tl + 2 < TC) RW_LV(P, tl + 2);
.LBB0_770:
	s_or_b64 exec, exec, s[8:9]
	s_cmp_gt_u32 s18, 29
	s_cselect_b64 s[8:9], -1, 0
	s_cbranch_scc1 .LBB0_772
	ds_read_b128 v[6:9], v114 offset:4608
	ds_read_b128 v[2:5], v114 offset:4624
	ds_read_b128 v[38:41], v114 offset:4864
	ds_read_b128 v[34:37], v114 offset:4880
	ds_read_b128 v[22:25], v114 offset:5120
	ds_read_b128 v[18:21], v114 offset:5136
	ds_read_b128 v[30:33], v114 offset:5376
	ds_read_b128 v[26:29], v114 offset:5392
	v_add_u32_e32 v10, 0x1000, v85
	ds_read2_b32 v[82:83], v10 offset0:128 offset1:160
	ds_read_b128 v[14:17], v114 offset:5632
	ds_read_b128 v[10:13], v114 offset:5648
	s_waitcnt lgkmcnt(2)
	v_mov_b32_e32 v84, v83
